# v26 plus: GEMM phase prologue issues K-tile 1 LDS-DMA loads before the first wait (vmcnt(8) instead of vmcnt(2) then loads)
# baseline (speedup 1.0000x reference)
.LBB0_24:
	v_lshrrev_b32_e32 v24, 1, v10
	v_and_b32_e32 v24, 24, v24
	v_and_b32_e32 v23, 15, v10
	v_lshlrev_b32_e32 v25, 1, v24
	v_lshlrev_b32_e32 v10, 2, v10
	v_lshl_or_b32 v17, s7, 6, v23
	v_lshl_or_b32 v23, v23, 6, v25
	s_lshl_b32 s0, s7, 13
	v_and_b32_e32 v10, 32, v10
	v_bitop3_b32 v25, v23, s0, v10 bitop3:0xde
	s_lshl_b32 s0, s8, 5
	s_and_b32 s8, s0, 0x60
	s_lshl_b32 s0, s8, 7
	v_bitop3_b32 v168, v23, s0, v10 bitop3:0xde
	v_readlane_b32 s0, v255, 28
	s_add_i32 m0, s25, 0x18000
	v_lshl_add_u64 v[8:9], v[8:9], 0, s[36:37]
	s_ashr_i32 s44, s0, 31
	global_load_lds_dwordx4 v[8:9], off
	v_lshl_add_u64 v[6:7], v[6:7], 0, s[36:37]
	s_add_i32 m0, s25, 0x1a000
	s_add_i32 s45, s25, 0x8000
	s_add_i32 s46, s25, 0xa000
	global_load_lds_dwordx4 v[6:7], off
	v_lshl_add_u64 v[2:3], v[2:3], 0, s[36:37]
	s_mov_b32 m0, s45
	s_add_u32 s0, s18, 0xc0080
	global_load_lds_dwordx4 v[2:3], off
	v_lshl_add_u64 v[2:3], v[4:5], 0, s[36:37]
	s_mov_b32 m0, s46
	s_addc_u32 s1, s19, 0
	global_load_lds_dwordx4 v[2:3], off
	s_add_i32 m0, s25, 0x1c000
	v_lshl_add_u64 v[2:3], s[0:1], 0, v[0:1]
	global_load_lds_dwordx4 v[2:3], off
	v_lshl_add_u64 v[2:3], s[0:1], 0, v[136:137]
	s_add_i32 m0, s25, 0x1e000
	s_movk_i32 s9, 0xc00
	global_load_lds_dwordx4 v[2:3], off
	s_waitcnt vmcnt(8)
	s_barrier
	v_or_b32_e32 v169, s8, v24
	v_lshrrev_b32_e32 v3, 1, v11
	v_mul_lo_u32 v2, v13, s9
	s_mov_b32 s8, 0xc000
	v_mad_u64_u32 v[2:3], s[0:1], v3, s8, v[2:3]
	v_or_b32_e32 v2, v2, v12
	v_add_lshl_u32 v2, v2, v18, 1
	v_mov_b32_e32 v3, v1
	s_mov_b64 s[10:11], 0xc0080
	v_lshl_add_u64 v[138:139], v[2:3], 0, s[10:11]
	v_lshrrev_b32_e32 v3, 1, v19
	v_mul_lo_u32 v2, v21, s9
	v_mad_u64_u32 v[2:3], s[0:1], v3, s8, v[2:3]
	v_or_b32_e32 v2, v2, v20
	s_waitcnt vmcnt(6)
	v_add_lshl_u32 v2, v2, v22, 1
	v_mov_b32_e32 v3, v1
	s_cmpk_lt_u32 s6, 0x100
	v_lshl_add_u64 v[140:141], v[2:3], 0, s[10:11]
	v_mov_b32_e32 v2, 0
	s_cselect_b64 s[6:7], -1, 0
	s_mov_b32 s47, 0
	v_add_u32_e32 v170, 0, v25
	v_mov_b32_e32 v3, v2
	v_mov_b32_e32 v4, v2
	v_mov_b32_e32 v5, v2
	v_mov_b32_e32 v6, v2
	v_mov_b32_e32 v7, v2
	v_mov_b32_e32 v8, v2
	v_mov_b32_e32 v9, v2
	v_mov_b32_e32 v10, v2
	v_mov_b32_e32 v11, v2
	v_mov_b32_e32 v12, v2
	v_mov_b32_e32 v13, v2
	v_mov_b32_e32 v18, v2
	v_mov_b32_e32 v19, v2
	v_mov_b32_e32 v20, v2
	v_mov_b32_e32 v21, v2
	v_mov_b32_e32 v22, v2
	v_mov_b32_e32 v23, v2
	v_mov_b32_e32 v24, v2
	v_mov_b32_e32 v25, v2
	v_mov_b32_e32 v26, v2
	v_mov_b32_e32 v27, v2
	v_mov_b32_e32 v28, v2
	v_mov_b32_e32 v29, v2
	v_mov_b32_e32 v30, v2
	v_mov_b32_e32 v31, v2
	v_mov_b32_e32 v32, v2
	v_mov_b32_e32 v33, v2
	v_mov_b32_e32 v34, v2
	v_mov_b32_e32 v35, v2
	v_mov_b32_e32 v36, v2
	v_mov_b32_e32 v37, v2
	v_mov_b32_e32 v38, v2
	v_mov_b32_e32 v39, v2
	v_mov_b32_e32 v40, v2
	v_mov_b32_e32 v41, v2
	v_mov_b32_e32 v42, v2
	v_mov_b32_e32 v43, v2
	v_mov_b32_e32 v44, v2
	v_mov_b32_e32 v45, v2
	v_mov_b32_e32 v46, v2
	v_mov_b32_e32 v47, v2
	v_mov_b32_e32 v48, v2
	v_mov_b32_e32 v49, v2
	v_mov_b32_e32 v50, v2
	v_mov_b32_e32 v51, v2
	v_mov_b32_e32 v52, v2
	v_mov_b32_e32 v53, v2
	v_mov_b32_e32 v54, v2
	v_mov_b32_e32 v55, v2
	v_mov_b32_e32 v56, v2
	v_mov_b32_e32 v57, v2
	v_mov_b32_e32 v58, v2
	v_mov_b32_e32 v59, v2
	v_mov_b32_e32 v60, v2
	v_mov_b32_e32 v61, v2
	v_mov_b32_e32 v62, v2
	v_mov_b32_e32 v63, v2
	v_mov_b32_e32 v64, v2
	v_mov_b32_e32 v65, v2
	v_mov_b32_e32 v66, v2
	v_mov_b32_e32 v67, v2
	v_mov_b32_e32 v68, v2
	v_mov_b32_e32 v69, v2
	v_mov_b32_e32 v70, v2
	v_mov_b32_e32 v71, v2
	v_mov_b32_e32 v72, v2
	v_mov_b32_e32 v73, v2
	v_mov_b32_e32 v74, v2
	v_mov_b32_e32 v75, v2
	v_mov_b32_e32 v76, v2
	v_mov_b32_e32 v77, v2
	v_mov_b32_e32 v78, v2
	v_mov_b32_e32 v79, v2
	v_mov_b32_e32 v80, v2
	v_mov_b32_e32 v81, v2
	v_mov_b32_e32 v82, v2
	v_mov_b32_e32 v83, v2
	v_mov_b32_e32 v84, v2
	v_mov_b32_e32 v85, v2
	v_mov_b32_e32 v86, v2
	v_mov_b32_e32 v87, v2
	v_mov_b32_e32 v88, v2
	v_mov_b32_e32 v89, v2
	v_mov_b32_e32 v90, v2
	v_mov_b32_e32 v91, v2
	v_mov_b32_e32 v92, v2
	v_mov_b32_e32 v93, v2
	v_mov_b32_e32 v94, v2
	v_mov_b32_e32 v95, v2
	v_mov_b32_e32 v96, v2
	v_mov_b32_e32 v97, v2
	v_mov_b32_e32 v98, v2
	v_mov_b32_e32 v99, v2
	v_mov_b32_e32 v100, v2
	v_mov_b32_e32 v101, v2
	v_mov_b32_e32 v102, v2
	v_mov_b32_e32 v103, v2
	v_mov_b32_e32 v104, v2
	v_mov_b32_e32 v105, v2
	v_mov_b32_e32 v106, v2
	v_mov_b32_e32 v107, v2
	v_mov_b32_e32 v108, v2
	v_mov_b32_e32 v109, v2
	v_mov_b32_e32 v110, v2
	v_mov_b32_e32 v111, v2
	v_mov_b32_e32 v112, v2
	v_mov_b32_e32 v113, v2
	v_mov_b32_e32 v114, v2
	v_mov_b32_e32 v115, v2
	v_mov_b32_e32 v116, v2
	v_mov_b32_e32 v117, v2
	v_mov_b32_e32 v118, v2
	v_mov_b32_e32 v119, v2
	v_mov_b32_e32 v120, v2
	v_mov_b32_e32 v121, v2
	v_mov_b32_e32 v122, v2
	v_mov_b32_e32 v123, v2
	v_mov_b32_e32 v124, v2
	v_mov_b32_e32 v125, v2
	v_mov_b32_e32 v126, v2
	v_mov_b32_e32 v127, v2
	v_mov_b32_e32 v128, v2
	v_mov_b32_e32 v129, v2
	v_mov_b32_e32 v130, v2
	v_mov_b32_e32 v131, v2
	v_mov_b32_e32 v132, v2
	v_mov_b32_e32 v133, v2
	s_barrier
	s_branch .LBB0_27

.LBB0_158:
	s_lshl_b64 s[6:7], s[70:71], 18
	v_readlane_b32 s5, v253, 8
	s_mov_b64 s[10:11], s[70:71]
	s_add_u32 s8, s5, s6
	v_readlane_b32 s5, v253, 9
	s_addc_u32 s9, s5, s7
	s_lshl_b32 s6, s10, 13
	s_ashr_i32 s7, s6, 31
	v_readlane_b32 s52, v254, 47
	v_and_b32_e32 v19, 15, v10
	s_lshl_b64 s[6:7], s[6:7], 2
	v_readlane_b32 s60, v254, 55
	v_bfe_u32 v20, v10, 4, 2
	v_lshl_or_b32 v17, s1, 6, v19
	v_readlane_b32 s61, v254, 56
	v_readlane_b32 s64, v254, 59
	v_readlane_b32 s65, v254, 60
	s_add_u32 s5, s60, s6
	v_lshlrev_b32_e32 v21, 4, v20
	v_lshlrev_b32_e32 v22, 2, v17
	s_mov_b64 s[64:65], s[8:9]
	s_addc_u32 s8, s61, s7
	s_lshl_b32 s93, s10, 20
	s_and_b32 s0, s0, 3
	v_lshl_or_b32 v21, v19, 6, v21
	s_lshl_b32 s6, s1, 13
	v_and_b32_e32 v23, 32, v22
	v_lshlrev_b32_e32 v10, 2, v10
	s_add_i32 m0, s79, 0x18000
	v_lshl_add_u64 v[8:9], v[8:9], 0, s[36:37]
	s_add_i32 s93, s93, 0x100000
	v_bitop3_b32 v23, v21, s6, v23 bitop3:0xde
	s_lshl_b32 s26, s0, 5
	s_lshl_b32 s6, s0, 12
	v_and_b32_e32 v10, 32, v10
	global_load_lds_dwordx4 v[8:9], off
	v_lshl_add_u64 v[6:7], v[6:7], 0, s[36:37]
	s_add_i32 m0, s79, 0x1a000
	s_add_i32 s94, s79, 0x8000
	s_add_i32 s95, s79, 0xa000
	v_bitop3_b32 v172, v21, s6, v10 bitop3:0xde
	global_load_lds_dwordx4 v[6:7], off
	v_lshl_add_u64 v[2:3], v[2:3], 0, s[36:37]
	s_mov_b32 m0, s94
	s_add_u32 s6, s24, 0x80080
	global_load_lds_dwordx4 v[2:3], off
	v_lshl_add_u64 v[2:3], v[4:5], 0, s[36:37]
	s_mov_b32 m0, s95
	s_addc_u32 s7, s25, 0
	global_load_lds_dwordx4 v[2:3], off
	s_add_i32 m0, s79, 0x1c000
	v_lshl_add_u64 v[2:3], s[6:7], 0, v[0:1]
	global_load_lds_dwordx4 v[2:3], off
	v_lshl_add_u64 v[2:3], s[6:7], 0, v[154:155]
	s_add_i32 m0, s79, 0x1e000
	s_cmpk_lt_u32 s3, 0x100
	global_load_lds_dwordx4 v[2:3], off
	s_waitcnt vmcnt(8)
	s_barrier
	s_cselect_b64 s[10:11], -1, 0
	s_lshl_b32 s1, s1, 4
	s_lshl_b32 s9, s0, 2
	s_or_b32 s1, s9, s1
	v_or_b32_e32 v2, s1, v20
	v_lshl_or_b32 v173, v2, 4, v19
	v_cmp_eq_u32_e64 s[6:7], 0, v173
	v_readlane_b32 s66, v254, 61
	v_readlane_b32 s67, v254, 62
	v_writelane_b32 v255, s6, 37
	s_movk_i32 s1, 0x100
	v_cmp_gt_i32_e64 s[66:67], s1, v173
	v_writelane_b32 v255, s7, 38
	s_ashr_i32 s6, s35, 31
	v_readlane_b32 s1, v255, 28
	s_ashr_i32 s7, s1, 31
	s_lshl_b32 s16, s0, 7
	s_add_u32 s0, s40, s16
	s_addc_u32 s1, s41, 0
	v_lshlrev_b32_e32 v2, 5, v20
	v_mov_b32_e32 v3, v1
	v_lshl_add_u64 v[158:159], s[0:1], 0, v[2:3]
	s_add_u32 s0, s5, s16
	s_addc_u32 s1, s8, 0
	s_lshl_b32 s38, s4, 2
	s_abs_i32 s39, s38
	v_lshl_add_u64 v[160:161], s[0:1], 0, v[2:3]
	v_cvt_f32_u32_e32 v2, s39
	v_or_b32_e32 v4, 16, v17
	v_or_b32_e32 v5, 32, v17
	v_or_b32_e32 v6, 48, v17
	v_rcp_iflag_f32_e32 v2, v2
	v_add_u32_e32 v7, 0x80, v17
	v_add_u32_e32 v8, 0x90, v17
	v_add_u32_e32 v9, 0xa0, v17
	v_mul_f32_e32 v2, 0x4f7ffffe, v2
	v_cvt_u32_f32_e32 v2, v2
	v_add_u32_e32 v10, 0xb0, v17
	v_readlane_b32 s1, v255, 1
	v_and_b32_e32 v3, 1, v11
	v_readlane_b32 s0, v255, 0
	v_lshl_add_u32 v175, v17, 5, s1
	v_lshl_add_u32 v178, v4, 5, s1
	v_lshl_add_u32 v181, v5, 5, s1
	v_lshl_add_u32 v184, v6, 5, s1
	v_lshl_add_u32 v187, v7, 5, s1
	v_lshl_add_u32 v190, v8, 5, s1
	v_lshl_add_u32 v193, v9, 5, s1
	v_lshl_add_u32 v196, v10, 5, s1
	v_readfirstlane_b32 s1, v2
	v_lshlrev_b32_e32 v2, 15, v11
	v_and_b32_e32 v2, 0xffff0000, v2
	v_lshl_add_u32 v2, v12, 12, v2
	v_lshl_or_b32 v2, v3, 6, v2
	v_lshl_add_u32 v162, v13, 1, v2
	v_lshlrev_b32_e32 v2, 15, v14
	v_add_u32_e32 v174, s0, v22
	v_lshl_add_u32 v177, v4, 2, s0
	v_lshl_add_u32 v180, v5, 2, s0
	v_lshl_add_u32 v183, v6, 2, s0
	v_lshl_add_u32 v186, v7, 2, s0
	v_lshl_add_u32 v189, v8, 2, s0
	v_lshl_add_u32 v192, v9, 2, s0
	v_lshl_add_u32 v195, v10, 2, s0
	s_sub_i32 s0, 0, s39
	v_and_b32_e32 v2, 0xffff0000, v2
	v_readlane_b32 s58, v254, 53
	v_readlane_b32 s59, v254, 54
	s_waitcnt vmcnt(6)
	s_mul_i32 s0, s0, s1
	v_lshl_add_u32 v2, v15, 12, v2
	v_and_b32_e32 v3, 1, v14
	v_readlane_b32 s55, v254, 50
	v_readlane_b32 s56, v254, 51
	v_readlane_b32 s62, v254, 57
	v_readlane_b32 s63, v254, 58
	s_mul_hi_u32 s0, s1, s0
	v_lshl_or_b32 v2, v3, 6, v2
	v_readlane_b32 s58, v253, 12
	v_lshlrev_b32_e32 v156, 3, v20
	s_mov_b32 s80, 0
	v_cmp_eq_u32_e64 s[42:43], 0, v20
	s_mov_b32 s27, s87
	v_mov_b32_e32 v157, v1
	s_mov_b32 s3, s87
	s_mov_b64 s[60:61], s[40:41]
	v_add_u32_e32 v176, s9, v175
	v_add_u32_e32 v179, s9, v178
	v_add_u32_e32 v182, s9, v181
	v_add_u32_e32 v185, s9, v184
	v_add_u32_e32 v188, s9, v187
	v_add_u32_e32 v191, s9, v190
	v_add_u32_e32 v194, s9, v193
	v_add_u32_e32 v197, s9, v196
	s_bfe_i32 s40, s4, 0x1001d
	s_add_i32 s41, s1, s0
	v_mov_b32_e32 v163, v1
	v_lshl_add_u32 v164, v18, 1, v2
	v_mov_b32_e32 v165, v1
	v_add_u32_e32 v198, 0, v23
	s_mov_b32 s56, 0xa400
	v_readlane_b32 s59, v253, 13
	v_readlane_b32 s55, v255, 2
	s_mov_b64 s[62:63], s[44:45]
	v_readlane_b32 s53, v254, 48
	v_readlane_b32 s54, v254, 49
	v_readlane_b32 s57, v254, 52
	s_barrier
	s_branch .LBB0_161

.LBB0_746:
	s_sub_i32 s1, s74, 21
	s_cmp_lt_u32 s1, -5
	s_cselect_b64 s[4:5], -1, 0
	s_add_i32 s1, s74, 3
	v_readlane_b32 s68, v254, 47
	v_readlane_b32 s69, v254, 48
	v_readlane_b32 s70, v254, 49
	v_readlane_b32 s71, v254, 50
	v_readlane_b32 s72, v254, 51
	v_readlane_b32 s73, v254, 52
	v_readlane_b32 s74, v254, 53
	v_readlane_b32 s75, v254, 54
	v_readlane_b32 s76, v254, 55
	v_readlane_b32 s77, v254, 56
	v_readlane_b32 s78, v254, 57
	v_readlane_b32 s79, v254, 58
	v_readlane_b32 s80, v254, 59
	v_readlane_b32 s81, v254, 60
	v_readlane_b32 s82, v254, 61
	v_readlane_b32 s83, v254, 62
	s_mov_b64 s[64:65], s[68:69]
	s_mov_b64 s[68:69], s[72:73]
	s_mov_b64 s[70:71], s[74:75]
	s_mov_b64 s[72:73], s[76:77]
	s_mov_b64 s[74:75], s[78:79]
	s_mov_b64 s[76:77], s[80:81]
	s_mov_b64 s[78:79], s[82:83]
	v_readlane_b32 s68, v255, 29
	s_cmp_lt_u32 s1, 9
	v_readlane_b32 s70, v255, 31
	v_readlane_b32 s71, v255, 32
	s_cselect_b32 s7, s65, s71
	s_cselect_b32 s6, s64, s70
	s_mov_b64 s[82:83], s[8:9]
	s_lshl_b64 s[8:9], s[8:9], 18
	v_readlane_b32 s1, v253, 8
	s_add_u32 s1, s1, s8
	v_readlane_b32 s8, v253, 9
	s_addc_u32 s9, s8, s9
	v_bfe_u32 v22, v11, 4, 2
	s_add_u32 s8, s1, 0x40000
	v_and_b32_e32 v21, 15, v11
	v_lshlrev_b32_e32 v23, 4, v22
	v_lshlrev_b32_e32 v11, 2, v11
	s_addc_u32 s9, s9, 0
	s_and_b32 s1, s11, 3
	v_lshl_or_b32 v23, v21, 6, v23
	s_lshl_b32 s11, s16, 13
	v_and_b32_e32 v11, 32, v11
	s_add_i32 m0, s50, 0x18000
	v_lshl_add_u64 v[8:9], v[8:9], 0, s[36:37]
	v_bitop3_b32 v24, v23, s11, v11 bitop3:0xde
	s_lshl_b32 s11, s1, 12
	global_load_lds_dwordx4 v[8:9], off
	v_lshl_add_u64 v[6:7], v[6:7], 0, s[36:37]
	s_add_i32 m0, s50, 0x1a000
	s_add_i32 s56, s50, 0x8000
	s_add_i32 s57, s50, 0xa000
	global_load_lds_dwordx4 v[6:7], off
	v_lshl_add_u64 v[2:3], v[2:3], 0, s[36:37]
	s_mov_b32 m0, s56
	s_add_u32 s18, s44, 0x80080
	global_load_lds_dwordx4 v[2:3], off
	v_lshl_add_u64 v[2:3], v[4:5], 0, s[36:37]
	s_mov_b32 m0, s57
	s_addc_u32 s19, s45, 0
	global_load_lds_dwordx4 v[2:3], off
	s_add_i32 m0, s50, 0x1c000
	v_lshl_add_u64 v[2:3], s[18:19], 0, v[0:1]
	global_load_lds_dwordx4 v[2:3], off
	v_lshl_add_u64 v[2:3], s[18:19], 0, v[14:15]
	s_add_i32 m0, s50, 0x1e000
	s_cmpk_lt_u32 s10, 0x100
	global_load_lds_dwordx4 v[2:3], off
	s_waitcnt vmcnt(8)
	s_barrier
	v_lshlrev_b32_e32 v3, 15, v10
	v_lshlrev_b32_e32 v2, 2, v22
	v_and_b32_e32 v3, 0xffff0000, v3
	v_lshl_or_b32 v17, s16, 6, v21
	v_bitop3_b32 v148, v23, s11, v11 bitop3:0xde
	s_cselect_b64 s[10:11], -1, 0
	v_lshl_or_b32 v149, s1, 5, v2
	s_lshl_b32 s16, s16, 4
	s_lshl_b32 s1, s1, 2
	v_lshl_add_u32 v3, v12, 12, v3
	v_and_b32_e32 v4, 1, v10
	s_or_b32 s16, s1, s16
	v_lshl_or_b32 v3, v4, 6, v3
	v_or_b32_e32 v2, s16, v22
	v_lshl_add_u32 v134, v13, 1, v3
	v_lshlrev_b32_e32 v3, 15, v18
	v_lshl_or_b32 v150, v2, 4, v21
	v_and_b32_e32 v3, 0xffff0000, v3
	s_waitcnt vmcnt(6)
	s_movk_i32 s16, 0x100
	v_lshlrev_b32_e32 v2, 4, v150
	s_add_i32 s1, s1, 0
	v_lshl_add_u32 v3, v19, 12, v3
	v_and_b32_e32 v4, 1, v18
	v_cmp_gt_i32_e32 vcc, s16, v150
	v_readlane_b32 s16, v255, 28
	s_add_i32 s1, s1, 0x20000
	v_lshl_or_b32 v3, v4, 6, v3
	v_add_u32_e32 v2, 0, v2
	v_readlane_b32 s80, v255, 24
	v_readlane_b32 s69, v255, 30
	v_readlane_b32 s72, v255, 33
	v_readlane_b32 s73, v255, 34
	v_readlane_b32 s74, v255, 35
	v_readlane_b32 s75, v255, 36
	s_mov_b32 s58, 0
	v_cmp_eq_u32_e64 s[38:39], 0, v22
	s_ashr_i32 s59, s35, 31
	s_ashr_i32 s60, s16, 31
	v_lshl_add_u32 v151, v17, 4, s1
	s_and_b64 s[16:17], s[4:5], vcc
	v_mov_b32_e32 v135, v1
	v_lshl_add_u32 v136, v20, 1, v3
	v_mov_b32_e32 v137, v1
	v_add_u32_e32 v152, 0, v24
	v_add_u32_e32 v153, 0x20000, v2
	v_readlane_b32 s81, v255, 25
	s_barrier
	s_branch .LBB0_749

.LBB0_862:
	s_lshl_b64 s[4:5], s[82:83], 18
	v_readlane_b32 s0, v253, 8
	s_add_u32 s4, s0, s4
	v_readlane_b32 s0, v253, 9
	s_addc_u32 s5, s0, s5
	v_writelane_b32 v255, s4, 41
	v_readlane_b32 s64, v254, 47
	s_lshl_b32 s0, s82, 10
	v_writelane_b32 v255, s5, 42
	s_lshl_b32 s4, s82, 13
	s_ashr_i32 s5, s4, 31
	s_lshl_b64 s[4:5], s[4:5], 2
	v_readlane_b32 s72, v254, 55
	v_readlane_b32 s73, v254, 56
	s_add_u32 s7, s72, s4
	s_addc_u32 s10, s73, s5
	s_lshl_b32 s3, s82, 20
	s_and_b32 s11, s2, 3
	s_add_i32 m0, s38, 0x18000
	v_lshl_add_u64 v[6:7], v[6:7], 0, s[36:37]
	s_add_i32 s86, s3, 0x100000
	s_lshl_b32 s12, s6, 13
	s_lshl_b32 s94, s11, 5
	s_lshl_b32 s15, s11, 12
	global_load_lds_dwordx4 v[6:7], off
	v_lshl_add_u64 v[4:5], v[4:5], 0, s[36:37]
	s_add_i32 m0, s38, 0x1a000
	s_add_i32 s2, s38, 0x8000
	s_add_i32 s3, s38, 0xa000
	global_load_lds_dwordx4 v[4:5], off
	v_lshl_add_u64 v[2:3], v[2:3], 0, s[36:37]
	s_mov_b32 m0, s2
	s_add_u32 s4, s20, 0x80080
	global_load_lds_dwordx4 v[2:3], off
	v_lshl_add_u64 v[2:3], v[8:9], 0, s[36:37]
	s_mov_b32 m0, s3
	s_addc_u32 s5, s21, 0
	global_load_lds_dwordx4 v[2:3], off
	s_add_i32 m0, s38, 0x1c000
	v_lshl_add_u64 v[2:3], s[4:5], 0, v[0:1]
	global_load_lds_dwordx4 v[2:3], off
	v_lshl_add_u64 v[2:3], s[4:5], 0, v[154:155]
	s_add_i32 m0, s38, 0x1e000
	v_and_b32_e32 v19, 15, v10
	global_load_lds_dwordx4 v[2:3], off
	s_waitcnt vmcnt(8)
	s_barrier
	v_bfe_u32 v20, v10, 4, 2
	v_lshl_or_b32 v17, s6, 6, v19
	v_lshlrev_b32_e32 v2, 4, v20
	v_lshlrev_b32_e32 v4, 2, v17
	v_readlane_b32 s74, v254, 57
	v_readlane_b32 s75, v254, 58
	v_lshl_or_b32 v2, v19, 6, v2
	v_and_b32_e32 v3, 32, v4
	s_cmpk_lt_u32 s1, 0x100
	v_bitop3_b32 v5, v2, s12, v3 bitop3:0xde
	v_lshlrev_b32_e32 v3, 2, v10
	s_cselect_b64 s[74:75], -1, 0
	s_lshl_b32 s1, s6, 4
	s_lshl_b32 s6, s11, 2
	v_and_b32_e32 v3, 32, v3
	s_or_b32 s1, s6, s1
	s_waitcnt vmcnt(0)
	v_bitop3_b32 v170, v2, s15, v3 bitop3:0xde
	v_or_b32_e32 v2, s1, v20
	v_lshl_or_b32 v171, v2, 4, v19
	s_movk_i32 s1, 0x100
	v_cmp_gt_i32_e64 s[4:5], s1, v171
	s_ashr_i32 s33, s35, 31
	v_lshlrev_b32_e32 v2, 5, v20
	v_writelane_b32 v255, s4, 43
	v_mov_b32_e32 v3, v1
	s_waitcnt vmcnt(6)
	v_or_b32_e32 v6, 16, v17
	v_writelane_b32 v255, s5, 44
	v_cmp_eq_u32_e64 s[4:5], 0, v171
	v_or_b32_e32 v7, 32, v17
	v_or_b32_e32 v8, 48, v17
	v_writelane_b32 v255, s4, 45
	v_add_u32_e32 v9, 0x80, v17
	v_add_u32_e32 v10, 0x90, v17
	v_writelane_b32 v255, s5, 46
	v_add_u32_e32 v19, 0xa0, v17
	v_readlane_b32 s1, v255, 28
	s_ashr_i32 s12, s1, 31
	s_lshl_b32 s1, s11, 7
	s_add_u32 s4, s7, s1
	s_addc_u32 s5, s10, 0
	v_lshl_add_u64 v[158:159], s[4:5], 0, v[2:3]
	v_lshlrev_b32_e32 v2, 15, v11
	v_and_b32_e32 v2, 0xffff0000, v2
	v_lshl_add_u32 v2, v12, 12, v2
	v_and_b32_e32 v3, 1, v11
	v_lshl_or_b32 v2, v3, 6, v2
	v_lshl_add_u32 v160, v13, 1, v2
	v_lshlrev_b32_e32 v2, 15, v14
	v_and_b32_e32 v2, 0xffff0000, v2
	v_add_u32_e32 v21, 0xb0, v17
	v_readlane_b32 s4, v255, 1
	v_lshl_add_u32 v2, v15, 12, v2
	v_and_b32_e32 v3, 1, v14
	v_readlane_b32 s1, v255, 0
	v_lshl_add_u32 v173, v17, 5, s4
	v_lshl_add_u32 v176, v6, 5, s4
	v_lshl_add_u32 v179, v7, 5, s4
	v_lshl_add_u32 v182, v8, 5, s4
	v_lshl_add_u32 v185, v9, 5, s4
	v_lshl_add_u32 v188, v10, 5, s4
	v_lshl_add_u32 v191, v19, 5, s4
	v_lshl_add_u32 v194, v21, 5, s4
	v_lshl_or_b32 v2, v3, 6, v2
	v_readlane_b32 s48, v253, 20
	v_readlane_b32 s72, v253, 26
	v_readlane_b32 s58, v253, 12
	v_lshlrev_b32_e32 v156, 3, v20
	s_mov_b32 s15, 0
	v_cmp_eq_u32_e64 s[42:43], 0, v20
	s_mov_b32 s95, s87
	v_mov_b32_e32 v157, v1
	v_add_u32_e32 v172, s1, v4
	v_add_u32_e32 v174, s6, v173
	v_lshl_add_u32 v175, v6, 2, s1
	v_add_u32_e32 v177, s6, v176
	v_lshl_add_u32 v178, v7, 2, s1
	v_add_u32_e32 v180, s6, v179
	v_lshl_add_u32 v181, v8, 2, s1
	v_add_u32_e32 v183, s6, v182
	v_lshl_add_u32 v184, v9, 2, s1
	v_add_u32_e32 v186, s6, v185
	v_lshl_add_u32 v187, v10, 2, s1
	v_add_u32_e32 v189, s6, v188
	v_lshl_add_u32 v190, v19, 2, s1
	v_add_u32_e32 v192, s6, v191
	v_lshl_add_u32 v193, v21, 2, s1
	v_add_u32_e32 v195, s6, v194
	v_mov_b32_e32 v161, v1
	v_lshl_add_u32 v162, v18, 1, v2
	v_mov_b32_e32 v163, v1
	v_add_u32_e32 v196, 0, v5
	v_readlane_b32 s49, v253, 21
	v_readlane_b32 s73, v253, 27
	v_readlane_b32 s59, v253, 13
	v_readlane_b32 s60, v255, 2
	v_readlane_b32 s65, v254, 48
	v_readlane_b32 s66, v254, 49
	v_readlane_b32 s67, v254, 50
	v_readlane_b32 s68, v254, 51
	v_readlane_b32 s69, v254, 52
	v_readlane_b32 s70, v254, 53
	v_readlane_b32 s71, v254, 54
	v_readlane_b32 s76, v254, 59
	v_readlane_b32 s77, v254, 60
	v_readlane_b32 s78, v254, 61
	v_readlane_b32 s79, v254, 62
	s_barrier
	s_branch .LBB0_865
